# row-wise phases work on the 4096-row band of the block's XCD class (bid%8), matching the GEMM phases' tile placement
# speedup vs baseline: 1.0191x; 1.0044x over previous
.LBB0_168:
	s_and_b64 vcc, exec, s[0:1]
	s_cbranch_vccz .LBB0_172
	s_and_b32 s101, s6, 7
	s_lshl_b32 s101, s101, 12
	s_lshr_b32 s4, s6, 3
	s_lshl_b32 s4, s4, 3
	s_add_i32 s4, s4, s101
	s_lshl_b32 s0, s38, 1
	s_add_i32 s4, s4, s0
	s_add_i32 s101, s101, 0xfff
	s_cmpk_gt_i32 s4, 0x7fff
	s_cbranch_scc1 .LBB0_172
	v_mbcnt_hi_u32_b32 v0, -1, v226
	v_and_b32_e32 v1, 64, v0
	v_add_u32_e32 v1, 64, v1
	v_xor_b32_e32 v2, 1, v0
	v_cmp_lt_i32_e32 vcc, v2, v1
	s_ashr_i32 s5, s4, 31
	s_mov_b32 s8, s92
	v_cndmask_b32_e32 v2, v0, v2, vcc
	v_lshlrev_b32_e32 v34, 2, v2
	v_xor_b32_e32 v2, 2, v0
	v_cmp_lt_i32_e32 vcc, v2, v1
	s_lshl_b64 s[0:1], s[4:5], 11
	s_add_u32 s0, s90, s0
	v_cndmask_b32_e32 v2, v0, v2, vcc
	v_lshlrev_b32_e32 v35, 2, v2
	v_xor_b32_e32 v2, 4, v0
	v_cmp_lt_i32_e32 vcc, v2, v1
	v_lshlrev_b32_e32 v8, 3, v64
	s_addc_u32 s1, s91, s1
	v_cndmask_b32_e32 v2, v0, v2, vcc
	v_lshlrev_b32_e32 v36, 2, v2
	v_xor_b32_e32 v2, 8, v0
	v_cmp_lt_i32_e32 vcc, v2, v1
	s_ashr_i32 s9, s8, 31
	s_lshl_b64 s[10:11], s[8:9], 11
	v_cndmask_b32_e32 v2, v0, v2, vcc
	v_lshlrev_b32_e32 v37, 2, v2
	v_xor_b32_e32 v2, 16, v0
	v_cmp_lt_i32_e32 vcc, v2, v1
	v_or_b32_e32 v4, 0x80, v64
	v_or_b32_e32 v6, 0xc0, v64
	v_cndmask_b32_e32 v2, v0, v2, vcc
	v_lshlrev_b32_e32 v38, 2, v2
	v_xor_b32_e32 v2, 32, v0
	v_cmp_lt_i32_e32 vcc, v2, v1
	v_mov_b32_e32 v1, 0
	v_mov_b32_e32 v9, v1
	v_lshl_add_u64 v[8:9], s[0:1], 0, v[8:9]
	s_mov_b64 s[0:1], 0x48f0e00
	v_lshl_add_u64 v[30:31], v[8:9], 0, s[0:1]
	s_lshl_b64 s[0:1], s[4:5], 12
	v_cndmask_b32_e32 v0, v0, v2, vcc
	s_add_u32 s0, s36, s0
	v_lshlrev_b32_e32 v39, 2, v0
	v_lshlrev_b32_e32 v0, 4, v64
	s_addc_u32 s1, s37, s1
	v_or_b32_e32 v2, 64, v64
	v_lshl_add_u64 v[28:29], s[44:45], 0, v[0:1]
	v_lshl_add_u64 v[0:1], s[0:1], 0, v[0:1]
	s_mov_b64 s[0:1], 0x1000
	v_lshl_add_u64 v[32:33], v[0:1], 0, s[0:1]
	s_lshl_b64 s[12:13], s[8:9], 12
	v_mov_b32_e32 v40, 0x358637bd
	s_mov_b32 s2, 0xf800000
	v_mov_b32_e32 v41, 0x260
	v_lshlrev_b32_e32 v42, 4, v64
	v_lshlrev_b32_e32 v43, 4, v2
	v_lshlrev_b32_e32 v44, 4, v4
	v_lshlrev_b32_e32 v45, 4, v6

.Lrms_loop:
	s_add_i32 s4, s4, s8
	s_min_i32 s5, s4, s101
	s_cmp_gt_i32 s4, s101
	s_cselect_b32 s0, 0, s12
	s_cselect_b32 s1, 0, s13
	v_lshl_add_u64 v[32:33], v[32:33], 0, s[0:1]
	s_ashr_i32 s0, s5, 11
	s_mul_i32 s0, s0, 6
	s_lshl_b32 s0, s0, 12
	s_add_u32 s14, s90, s0
	s_addc_u32 s15, s91, 0
	s_add_u32 s16, s14, 0x1000
	s_addc_u32 s17, s15, 0
	global_load_dwordx4 v[80:83], v[32:33], off offset:-4096 nt
	global_load_dwordx4 v[84:87], v[32:33], off offset:-3072 nt
	global_load_dwordx4 v[88:91], v[32:33], off offset:-2048 nt
	global_load_dwordx4 v[92:95], v[32:33], off offset:-1024 nt
	global_load_dwordx4 v[96:99], v[32:33], off nt
	global_load_dwordx4 v[100:103], v[32:33], off offset:1024 nt
	global_load_dwordx4 v[104:107], v[32:33], off offset:2048 nt
	global_load_dwordx4 v[108:111], v[32:33], off offset:3072 nt
	global_load_dwordx4 v[160:163], v42, s[14:15]
	global_load_dwordx4 v[164:167], v42, s[14:15] offset:1024
	global_load_dwordx4 v[168:171], v42, s[14:15] offset:2048
	global_load_dwordx4 v[172:175], v42, s[14:15] offset:3072
	global_load_dwordx4 v[176:179], v42, s[16:17]
	global_load_dwordx4 v[180:183], v42, s[16:17] offset:1024
	global_load_dwordx4 v[184:187], v42, s[16:17] offset:2048
	global_load_dwordx4 v[188:191], v42, s[16:17] offset:3072
	s_waitcnt vmcnt(24)
	v_pk_mul_f32 v[0:1], v[48:49], v[48:49]
	v_pk_fma_f32 v[0:1], v[50:51], v[50:51], v[0:1]
	v_pk_fma_f32 v[0:1], v[52:53], v[52:53], v[0:1]
	v_pk_fma_f32 v[0:1], v[54:55], v[54:55], v[0:1]
	v_pk_fma_f32 v[0:1], v[56:57], v[56:57], v[0:1]
	v_pk_fma_f32 v[0:1], v[58:59], v[58:59], v[0:1]
	v_pk_fma_f32 v[0:1], v[60:61], v[60:61], v[0:1]
	v_pk_fma_f32 v[0:1], v[62:63], v[62:63], v[0:1]
	v_pk_mul_f32 v[2:3], v[64:65], v[64:65]
	v_pk_fma_f32 v[2:3], v[66:67], v[66:67], v[2:3]
	v_pk_fma_f32 v[2:3], v[68:69], v[68:69], v[2:3]
	v_pk_fma_f32 v[2:3], v[70:71], v[70:71], v[2:3]
	v_pk_fma_f32 v[2:3], v[72:73], v[72:73], v[2:3]
	v_pk_fma_f32 v[2:3], v[74:75], v[74:75], v[2:3]
	v_pk_fma_f32 v[2:3], v[76:77], v[76:77], v[2:3]
	v_pk_fma_f32 v[2:3], v[78:79], v[78:79], v[2:3]
	v_add_f32_e32 v0, v0, v1
	v_add_f32_e32 v2, v2, v3
	ds_bpermute_b32 v1, v34, v0
	ds_bpermute_b32 v3, v34, v2
	s_waitcnt lgkmcnt(0)
	v_add_f32_e32 v0, v0, v1
	v_add_f32_e32 v2, v2, v3
	ds_bpermute_b32 v1, v35, v0
	ds_bpermute_b32 v3, v35, v2
	s_waitcnt lgkmcnt(0)
	v_add_f32_e32 v0, v0, v1
	v_add_f32_e32 v2, v2, v3
	ds_bpermute_b32 v1, v36, v0
	ds_bpermute_b32 v3, v36, v2
	s_waitcnt lgkmcnt(0)
	v_add_f32_e32 v0, v0, v1
	v_add_f32_e32 v2, v2, v3
	ds_bpermute_b32 v1, v37, v0
	ds_bpermute_b32 v3, v37, v2
	s_waitcnt lgkmcnt(0)
	v_add_f32_e32 v0, v0, v1
	v_add_f32_e32 v2, v2, v3
	ds_bpermute_b32 v1, v38, v0
	ds_bpermute_b32 v3, v38, v2
	s_waitcnt lgkmcnt(0)
	v_add_f32_e32 v0, v0, v1
	v_add_f32_e32 v2, v2, v3
	ds_bpermute_b32 v1, v39, v0
	ds_bpermute_b32 v3, v39, v2
	s_waitcnt lgkmcnt(0)
	v_add_f32_e32 v0, v0, v1
	v_add_f32_e32 v2, v2, v3
	v_fmamk_f32 v0, v0, 0x3a800000, v40
	v_mul_f32_e32 v4, 0x4f800000, v0
	v_cmp_gt_f32_e32 vcc, s2, v0
	s_nop 1
	v_cndmask_b32_e32 v0, v0, v4, vcc
	v_sqrt_f32_e32 v4, v0
	s_nop 0
	v_add_u32_e32 v5, -1, v4
	v_add_u32_e32 v6, 1, v4
	v_fma_f32 v7, -v5, v4, v0
	v_fma_f32 v8, -v6, v4, v0
	v_cmp_ge_f32_e64 s[0:1], 0, v7
	s_nop 1
	v_cndmask_b32_e64 v4, v4, v5, s[0:1]
	v_cmp_lt_f32_e64 s[0:1], 0, v8
	s_nop 1
	v_cndmask_b32_e64 v4, v4, v6, s[0:1]
	v_mul_f32_e32 v5, 0x37800000, v4
	v_cndmask_b32_e32 v4, v4, v5, vcc
	v_cmp_class_f32_e32 vcc, v0, v41
	s_nop 1
	v_cndmask_b32_e32 v0, v4, v0, vcc
	v_div_scale_f32 v4, s[0:1], v0, v0, 1.0
	v_rcp_f32_e32 v6, v4
	v_div_scale_f32 v5, vcc, 1.0, v0, 1.0
	v_fma_f32 v7, -v4, v6, 1.0
	v_fmac_f32_e32 v6, v7, v6
	v_mul_f32_e32 v7, v5, v6
	v_fma_f32 v8, -v4, v7, v5
	v_fmac_f32_e32 v7, v8, v6
	v_fma_f32 v4, -v4, v7, v5
	v_div_fmas_f32 v4, v4, v6, v7
	v_div_fixup_f32 v0, v4, v0, 1.0
	v_fmamk_f32 v2, v2, 0x3a800000, v40
	v_mul_f32_e32 v10, 0x4f800000, v2
	v_cmp_gt_f32_e32 vcc, s2, v2
	s_nop 1
	v_cndmask_b32_e32 v2, v2, v10, vcc
	v_sqrt_f32_e32 v10, v2
	s_nop 0
	v_add_u32_e32 v11, -1, v10
	v_add_u32_e32 v12, 1, v10
	v_fma_f32 v13, -v11, v10, v2
	v_fma_f32 v14, -v12, v10, v2
	v_cmp_ge_f32_e64 s[0:1], 0, v13
	s_nop 1
	v_cndmask_b32_e64 v10, v10, v11, s[0:1]
	v_cmp_lt_f32_e64 s[0:1], 0, v14
	s_nop 1
	v_cndmask_b32_e64 v10, v10, v12, s[0:1]
	v_mul_f32_e32 v11, 0x37800000, v10
	v_cndmask_b32_e32 v10, v10, v11, vcc
	v_cmp_class_f32_e32 vcc, v2, v41
	s_nop 1
	v_cndmask_b32_e32 v2, v10, v2, vcc
	v_div_scale_f32 v10, s[0:1], v2, v2, 1.0
	v_rcp_f32_e32 v12, v10
	v_div_scale_f32 v11, vcc, 1.0, v2, 1.0
	v_fma_f32 v13, -v10, v12, 1.0
	v_fmac_f32_e32 v12, v13, v12
	v_mul_f32_e32 v13, v11, v12
	v_fma_f32 v14, -v10, v13, v11
	v_fmac_f32_e32 v13, v14, v12
	v_fma_f32 v10, -v10, v13, v11
	v_div_fmas_f32 v10, v10, v12, v13
	v_div_fixup_f32 v2, v10, v2, 1.0
	v_pk_add_f32 v[144:145], v[144:145], 1.0 op_sel_hi:[1,0]
	v_pk_add_f32 v[146:147], v[146:147], 1.0 op_sel_hi:[1,0]
	v_pk_add_f32 v[148:149], v[148:149], 1.0 op_sel_hi:[1,0]
	v_pk_add_f32 v[150:151], v[150:151], 1.0 op_sel_hi:[1,0]
	v_pk_add_f32 v[152:153], v[152:153], 1.0 op_sel_hi:[1,0]
	v_pk_add_f32 v[154:155], v[154:155], 1.0 op_sel_hi:[1,0]
	v_pk_add_f32 v[156:157], v[156:157], 1.0 op_sel_hi:[1,0]
	v_pk_add_f32 v[158:159], v[158:159], 1.0 op_sel_hi:[1,0]
	v_pk_mul_f32 v[48:49], v[48:49], v[0:1] op_sel_hi:[1,0]
	v_pk_mul_f32 v[50:51], v[50:51], v[0:1] op_sel_hi:[1,0]
	v_pk_mul_f32 v[48:49], v[112:113], v[48:49]
	v_pk_mul_f32 v[50:51], v[114:115], v[50:51]
	v_pk_fma_f32 v[48:49], v[144:145], v[48:49], v[128:129]
	v_pk_fma_f32 v[50:51], v[146:147], v[50:51], v[130:131]
	v_cvt_pk_bf16_f32 v48, v48, v49
	v_cvt_pk_bf16_f32 v49, v50, v51
	global_store_dwordx2 v[30:31], v[48:49], off offset:-3584
	v_pk_mul_f32 v[52:53], v[52:53], v[0:1] op_sel_hi:[1,0]
	v_pk_mul_f32 v[54:55], v[54:55], v[0:1] op_sel_hi:[1,0]
	v_pk_mul_f32 v[52:53], v[116:117], v[52:53]
	v_pk_mul_f32 v[54:55], v[118:119], v[54:55]
	v_pk_fma_f32 v[52:53], v[148:149], v[52:53], v[132:133]
	v_pk_fma_f32 v[54:55], v[150:151], v[54:55], v[134:135]
	v_cvt_pk_bf16_f32 v52, v52, v53
	v_cvt_pk_bf16_f32 v53, v54, v55
	global_store_dwordx2 v[30:31], v[52:53], off offset:-3072
	v_pk_mul_f32 v[56:57], v[56:57], v[0:1] op_sel_hi:[1,0]
	v_pk_mul_f32 v[58:59], v[58:59], v[0:1] op_sel_hi:[1,0]
	v_pk_mul_f32 v[56:57], v[120:121], v[56:57]
	v_pk_mul_f32 v[58:59], v[122:123], v[58:59]
	v_pk_fma_f32 v[56:57], v[152:153], v[56:57], v[136:137]
	v_pk_fma_f32 v[58:59], v[154:155], v[58:59], v[138:139]
	v_cvt_pk_bf16_f32 v56, v56, v57
	v_cvt_pk_bf16_f32 v57, v58, v59
	global_store_dwordx2 v[30:31], v[56:57], off offset:-2560
	v_pk_mul_f32 v[60:61], v[60:61], v[0:1] op_sel_hi:[1,0]
	v_pk_mul_f32 v[62:63], v[62:63], v[0:1] op_sel_hi:[1,0]
	v_pk_mul_f32 v[60:61], v[124:125], v[60:61]
	v_pk_mul_f32 v[62:63], v[126:127], v[62:63]
	v_pk_fma_f32 v[60:61], v[156:157], v[60:61], v[140:141]
	v_pk_fma_f32 v[62:63], v[158:159], v[62:63], v[142:143]
	v_cvt_pk_bf16_f32 v60, v60, v61
	v_cvt_pk_bf16_f32 v61, v62, v63
	global_store_dwordx2 v[30:31], v[60:61], off offset:-2048
	v_pk_mul_f32 v[64:65], v[64:65], v[2:3] op_sel_hi:[1,0]
	v_pk_mul_f32 v[66:67], v[66:67], v[2:3] op_sel_hi:[1,0]
	v_pk_mul_f32 v[64:65], v[112:113], v[64:65]
	v_pk_mul_f32 v[66:67], v[114:115], v[66:67]
	v_pk_fma_f32 v[64:65], v[144:145], v[64:65], v[128:129]
	v_pk_fma_f32 v[66:67], v[146:147], v[66:67], v[130:131]
	v_cvt_pk_bf16_f32 v64, v64, v65
	v_cvt_pk_bf16_f32 v65, v66, v67
	global_store_dwordx2 v[30:31], v[64:65], off offset:-1536
	v_pk_mul_f32 v[68:69], v[68:69], v[2:3] op_sel_hi:[1,0]
	v_pk_mul_f32 v[70:71], v[70:71], v[2:3] op_sel_hi:[1,0]
	v_pk_mul_f32 v[68:69], v[116:117], v[68:69]
	v_pk_mul_f32 v[70:71], v[118:119], v[70:71]
	v_pk_fma_f32 v[68:69], v[148:149], v[68:69], v[132:133]
	v_pk_fma_f32 v[70:71], v[150:151], v[70:71], v[134:135]
	v_cvt_pk_bf16_f32 v68, v68, v69
	v_cvt_pk_bf16_f32 v69, v70, v71
	global_store_dwordx2 v[30:31], v[68:69], off offset:-1024
	v_pk_mul_f32 v[72:73], v[72:73], v[2:3] op_sel_hi:[1,0]
	v_pk_mul_f32 v[74:75], v[74:75], v[2:3] op_sel_hi:[1,0]
	v_pk_mul_f32 v[72:73], v[120:121], v[72:73]
	v_pk_mul_f32 v[74:75], v[122:123], v[74:75]
	v_pk_fma_f32 v[72:73], v[152:153], v[72:73], v[136:137]
	v_pk_fma_f32 v[74:75], v[154:155], v[74:75], v[138:139]
	v_cvt_pk_bf16_f32 v72, v72, v73
	v_cvt_pk_bf16_f32 v73, v74, v75
	global_store_dwordx2 v[30:31], v[72:73], off offset:-512
	v_pk_mul_f32 v[76:77], v[76:77], v[2:3] op_sel_hi:[1,0]
	v_pk_mul_f32 v[78:79], v[78:79], v[2:3] op_sel_hi:[1,0]
	v_pk_mul_f32 v[76:77], v[124:125], v[76:77]
	v_pk_mul_f32 v[78:79], v[126:127], v[78:79]
	v_pk_fma_f32 v[76:77], v[156:157], v[76:77], v[140:141]
	v_pk_fma_f32 v[78:79], v[158:159], v[78:79], v[142:143]
	v_cvt_pk_bf16_f32 v76, v76, v77
	v_cvt_pk_bf16_f32 v77, v78, v79
	global_store_dwordx2 v[30:31], v[76:77], off
	v_lshl_add_u64 v[30:31], v[30:31], 0, s[10:11]
	s_cmp_gt_i32 s4, s101
	s_cbranch_scc1 .Lrms_exit
	s_add_i32 s4, s4, s8
	s_min_i32 s5, s4, s101
	s_cmp_gt_i32 s4, s101
	s_cselect_b32 s0, 0, s12
	s_cselect_b32 s1, 0, s13
	v_lshl_add_u64 v[32:33], v[32:33], 0, s[0:1]
	s_ashr_i32 s0, s5, 11
	s_mul_i32 s0, s0, 6
	s_lshl_b32 s0, s0, 12
	s_add_u32 s14, s90, s0
	s_addc_u32 s15, s91, 0
	s_add_u32 s16, s14, 0x1000
	s_addc_u32 s17, s15, 0
	global_load_dwordx4 v[48:51], v[32:33], off offset:-4096 nt
	global_load_dwordx4 v[52:55], v[32:33], off offset:-3072 nt
	global_load_dwordx4 v[56:59], v[32:33], off offset:-2048 nt
	global_load_dwordx4 v[60:63], v[32:33], off offset:-1024 nt
	global_load_dwordx4 v[64:67], v[32:33], off nt
	global_load_dwordx4 v[68:71], v[32:33], off offset:1024 nt
	global_load_dwordx4 v[72:75], v[32:33], off offset:2048 nt
	global_load_dwordx4 v[76:79], v[32:33], off offset:3072 nt
	global_load_dwordx4 v[128:131], v42, s[14:15]
	global_load_dwordx4 v[132:135], v42, s[14:15] offset:1024
	global_load_dwordx4 v[136:139], v42, s[14:15] offset:2048
	global_load_dwordx4 v[140:143], v42, s[14:15] offset:3072
	global_load_dwordx4 v[144:147], v42, s[16:17]
	global_load_dwordx4 v[148:151], v42, s[16:17] offset:1024
	global_load_dwordx4 v[152:155], v42, s[16:17] offset:2048
	global_load_dwordx4 v[156:159], v42, s[16:17] offset:3072
	s_waitcnt vmcnt(24)
	v_pk_mul_f32 v[0:1], v[80:81], v[80:81]
	v_pk_fma_f32 v[0:1], v[82:83], v[82:83], v[0:1]
	v_pk_fma_f32 v[0:1], v[84:85], v[84:85], v[0:1]
	v_pk_fma_f32 v[0:1], v[86:87], v[86:87], v[0:1]
	v_pk_fma_f32 v[0:1], v[88:89], v[88:89], v[0:1]
	v_pk_fma_f32 v[0:1], v[90:91], v[90:91], v[0:1]
	v_pk_fma_f32 v[0:1], v[92:93], v[92:93], v[0:1]
	v_pk_fma_f32 v[0:1], v[94:95], v[94:95], v[0:1]
	v_pk_mul_f32 v[2:3], v[96:97], v[96:97]
	v_pk_fma_f32 v[2:3], v[98:99], v[98:99], v[2:3]
	v_pk_fma_f32 v[2:3], v[100:101], v[100:101], v[2:3]
	v_pk_fma_f32 v[2:3], v[102:103], v[102:103], v[2:3]
	v_pk_fma_f32 v[2:3], v[104:105], v[104:105], v[2:3]
	v_pk_fma_f32 v[2:3], v[106:107], v[106:107], v[2:3]
	v_pk_fma_f32 v[2:3], v[108:109], v[108:109], v[2:3]
	v_pk_fma_f32 v[2:3], v[110:111], v[110:111], v[2:3]
	v_add_f32_e32 v0, v0, v1
	v_add_f32_e32 v2, v2, v3
	ds_bpermute_b32 v1, v34, v0
	ds_bpermute_b32 v3, v34, v2
	s_waitcnt lgkmcnt(0)
	v_add_f32_e32 v0, v0, v1
	v_add_f32_e32 v2, v2, v3
	ds_bpermute_b32 v1, v35, v0
	ds_bpermute_b32 v3, v35, v2
	s_waitcnt lgkmcnt(0)
	v_add_f32_e32 v0, v0, v1
	v_add_f32_e32 v2, v2, v3
	ds_bpermute_b32 v1, v36, v0
	ds_bpermute_b32 v3, v36, v2
	s_waitcnt lgkmcnt(0)
	v_add_f32_e32 v0, v0, v1
	v_add_f32_e32 v2, v2, v3
	ds_bpermute_b32 v1, v37, v0
	ds_bpermute_b32 v3, v37, v2
	s_waitcnt lgkmcnt(0)
	v_add_f32_e32 v0, v0, v1
	v_add_f32_e32 v2, v2, v3
	ds_bpermute_b32 v1, v38, v0
	ds_bpermute_b32 v3, v38, v2
	s_waitcnt lgkmcnt(0)
	v_add_f32_e32 v0, v0, v1
	v_add_f32_e32 v2, v2, v3
	ds_bpermute_b32 v1, v39, v0
	ds_bpermute_b32 v3, v39, v2
	s_waitcnt lgkmcnt(0)
	v_add_f32_e32 v0, v0, v1
	v_add_f32_e32 v2, v2, v3
	v_fmamk_f32 v0, v0, 0x3a800000, v40
	v_mul_f32_e32 v4, 0x4f800000, v0
	v_cmp_gt_f32_e32 vcc, s2, v0
	s_nop 1
	v_cndmask_b32_e32 v0, v0, v4, vcc
	v_sqrt_f32_e32 v4, v0
	s_nop 0
	v_add_u32_e32 v5, -1, v4
	v_add_u32_e32 v6, 1, v4
	v_fma_f32 v7, -v5, v4, v0
	v_fma_f32 v8, -v6, v4, v0
	v_cmp_ge_f32_e64 s[0:1], 0, v7
	s_nop 1
	v_cndmask_b32_e64 v4, v4, v5, s[0:1]
	v_cmp_lt_f32_e64 s[0:1], 0, v8
	s_nop 1
	v_cndmask_b32_e64 v4, v4, v6, s[0:1]
	v_mul_f32_e32 v5, 0x37800000, v4
	v_cndmask_b32_e32 v4, v4, v5, vcc
	v_cmp_class_f32_e32 vcc, v0, v41
	s_nop 1
	v_cndmask_b32_e32 v0, v4, v0, vcc
	v_div_scale_f32 v4, s[0:1], v0, v0, 1.0
	v_rcp_f32_e32 v6, v4
	v_div_scale_f32 v5, vcc, 1.0, v0, 1.0
	v_fma_f32 v7, -v4, v6, 1.0
	v_fmac_f32_e32 v6, v7, v6
	v_mul_f32_e32 v7, v5, v6
	v_fma_f32 v8, -v4, v7, v5
	v_fmac_f32_e32 v7, v8, v6
	v_fma_f32 v4, -v4, v7, v5
	v_div_fmas_f32 v4, v4, v6, v7
	v_div_fixup_f32 v0, v4, v0, 1.0
	v_fmamk_f32 v2, v2, 0x3a800000, v40
	v_mul_f32_e32 v10, 0x4f800000, v2
	v_cmp_gt_f32_e32 vcc, s2, v2
	s_nop 1
	v_cndmask_b32_e32 v2, v2, v10, vcc
	v_sqrt_f32_e32 v10, v2
	s_nop 0
	v_add_u32_e32 v11, -1, v10
	v_add_u32_e32 v12, 1, v10
	v_fma_f32 v13, -v11, v10, v2
	v_fma_f32 v14, -v12, v10, v2
	v_cmp_ge_f32_e64 s[0:1], 0, v13
	s_nop 1
	v_cndmask_b32_e64 v10, v10, v11, s[0:1]
	v_cmp_lt_f32_e64 s[0:1], 0, v14
	s_nop 1
	v_cndmask_b32_e64 v10, v10, v12, s[0:1]
	v_mul_f32_e32 v11, 0x37800000, v10
	v_cndmask_b32_e32 v10, v10, v11, vcc
	v_cmp_class_f32_e32 vcc, v2, v41
	s_nop 1
	v_cndmask_b32_e32 v2, v10, v2, vcc
	v_div_scale_f32 v10, s[0:1], v2, v2, 1.0
	v_rcp_f32_e32 v12, v10
	v_div_scale_f32 v11, vcc, 1.0, v2, 1.0
	v_fma_f32 v13, -v10, v12, 1.0
	v_fmac_f32_e32 v12, v13, v12
	v_mul_f32_e32 v13, v11, v12
	v_fma_f32 v14, -v10, v13, v11
	v_fmac_f32_e32 v13, v14, v12
	v_fma_f32 v10, -v10, v13, v11
	v_div_fmas_f32 v10, v10, v12, v13
	v_div_fixup_f32 v2, v10, v2, 1.0
	v_pk_add_f32 v[176:177], v[176:177], 1.0 op_sel_hi:[1,0]
	v_pk_add_f32 v[178:179], v[178:179], 1.0 op_sel_hi:[1,0]
	v_pk_add_f32 v[180:181], v[180:181], 1.0 op_sel_hi:[1,0]
	v_pk_add_f32 v[182:183], v[182:183], 1.0 op_sel_hi:[1,0]
	v_pk_add_f32 v[184:185], v[184:185], 1.0 op_sel_hi:[1,0]
	v_pk_add_f32 v[186:187], v[186:187], 1.0 op_sel_hi:[1,0]
	v_pk_add_f32 v[188:189], v[188:189], 1.0 op_sel_hi:[1,0]
	v_pk_add_f32 v[190:191], v[190:191], 1.0 op_sel_hi:[1,0]
	v_pk_mul_f32 v[80:81], v[80:81], v[0:1] op_sel_hi:[1,0]
	v_pk_mul_f32 v[82:83], v[82:83], v[0:1] op_sel_hi:[1,0]
	v_pk_mul_f32 v[80:81], v[112:113], v[80:81]
	v_pk_mul_f32 v[82:83], v[114:115], v[82:83]
	v_pk_fma_f32 v[80:81], v[176:177], v[80:81], v[160:161]
	v_pk_fma_f32 v[82:83], v[178:179], v[82:83], v[162:163]
	v_cvt_pk_bf16_f32 v80, v80, v81
	v_cvt_pk_bf16_f32 v81, v82, v83
	global_store_dwordx2 v[30:31], v[80:81], off offset:-3584
	v_pk_mul_f32 v[84:85], v[84:85], v[0:1] op_sel_hi:[1,0]
	v_pk_mul_f32 v[86:87], v[86:87], v[0:1] op_sel_hi:[1,0]
	v_pk_mul_f32 v[84:85], v[116:117], v[84:85]
	v_pk_mul_f32 v[86:87], v[118:119], v[86:87]
	v_pk_fma_f32 v[84:85], v[180:181], v[84:85], v[164:165]
	v_pk_fma_f32 v[86:87], v[182:183], v[86:87], v[166:167]
	v_cvt_pk_bf16_f32 v84, v84, v85
	v_cvt_pk_bf16_f32 v85, v86, v87
	global_store_dwordx2 v[30:31], v[84:85], off offset:-3072
	v_pk_mul_f32 v[88:89], v[88:89], v[0:1] op_sel_hi:[1,0]
	v_pk_mul_f32 v[90:91], v[90:91], v[0:1] op_sel_hi:[1,0]
	v_pk_mul_f32 v[88:89], v[120:121], v[88:89]
	v_pk_mul_f32 v[90:91], v[122:123], v[90:91]
	v_pk_fma_f32 v[88:89], v[184:185], v[88:89], v[168:169]
	v_pk_fma_f32 v[90:91], v[186:187], v[90:91], v[170:171]
	v_cvt_pk_bf16_f32 v88, v88, v89
	v_cvt_pk_bf16_f32 v89, v90, v91
	global_store_dwordx2 v[30:31], v[88:89], off offset:-2560
	v_pk_mul_f32 v[92:93], v[92:93], v[0:1] op_sel_hi:[1,0]
	v_pk_mul_f32 v[94:95], v[94:95], v[0:1] op_sel_hi:[1,0]
	v_pk_mul_f32 v[92:93], v[124:125], v[92:93]
	v_pk_mul_f32 v[94:95], v[126:127], v[94:95]
	v_pk_fma_f32 v[92:93], v[188:189], v[92:93], v[172:173]
	v_pk_fma_f32 v[94:95], v[190:191], v[94:95], v[174:175]
	v_cvt_pk_bf16_f32 v92, v92, v93
	v_cvt_pk_bf16_f32 v93, v94, v95
	global_store_dwordx2 v[30:31], v[92:93], off offset:-2048
	v_pk_mul_f32 v[96:97], v[96:97], v[2:3] op_sel_hi:[1,0]
	v_pk_mul_f32 v[98:99], v[98:99], v[2:3] op_sel_hi:[1,0]
	v_pk_mul_f32 v[96:97], v[112:113], v[96:97]
	v_pk_mul_f32 v[98:99], v[114:115], v[98:99]
	v_pk_fma_f32 v[96:97], v[176:177], v[96:97], v[160:161]
	v_pk_fma_f32 v[98:99], v[178:179], v[98:99], v[162:163]
	v_cvt_pk_bf16_f32 v96, v96, v97
	v_cvt_pk_bf16_f32 v97, v98, v99
	global_store_dwordx2 v[30:31], v[96:97], off offset:-1536
	v_pk_mul_f32 v[100:101], v[100:101], v[2:3] op_sel_hi:[1,0]
	v_pk_mul_f32 v[102:103], v[102:103], v[2:3] op_sel_hi:[1,0]
	v_pk_mul_f32 v[100:101], v[116:117], v[100:101]
	v_pk_mul_f32 v[102:103], v[118:119], v[102:103]
	v_pk_fma_f32 v[100:101], v[180:181], v[100:101], v[164:165]
	v_pk_fma_f32 v[102:103], v[182:183], v[102:103], v[166:167]
	v_cvt_pk_bf16_f32 v100, v100, v101
	v_cvt_pk_bf16_f32 v101, v102, v103
	global_store_dwordx2 v[30:31], v[100:101], off offset:-1024
	v_pk_mul_f32 v[104:105], v[104:105], v[2:3] op_sel_hi:[1,0]
	v_pk_mul_f32 v[106:107], v[106:107], v[2:3] op_sel_hi:[1,0]
	v_pk_mul_f32 v[104:105], v[120:121], v[104:105]
	v_pk_mul_f32 v[106:107], v[122:123], v[106:107]
	v_pk_fma_f32 v[104:105], v[184:185], v[104:105], v[168:169]
	v_pk_fma_f32 v[106:107], v[186:187], v[106:107], v[170:171]
	v_cvt_pk_bf16_f32 v104, v104, v105
	v_cvt_pk_bf16_f32 v105, v106, v107
	global_store_dwordx2 v[30:31], v[104:105], off offset:-512
	v_pk_mul_f32 v[108:109], v[108:109], v[2:3] op_sel_hi:[1,0]
	v_pk_mul_f32 v[110:111], v[110:111], v[2:3] op_sel_hi:[1,0]
	v_pk_mul_f32 v[108:109], v[124:125], v[108:109]
	v_pk_mul_f32 v[110:111], v[126:127], v[110:111]
	v_pk_fma_f32 v[108:109], v[188:189], v[108:109], v[172:173]
	v_pk_fma_f32 v[110:111], v[190:191], v[110:111], v[174:175]
	v_cvt_pk_bf16_f32 v108, v108, v109
	v_cvt_pk_bf16_f32 v109, v110, v111
	global_store_dwordx2 v[30:31], v[108:109], off
	v_lshl_add_u64 v[30:31], v[30:31], 0, s[10:11]
	s_cmp_gt_i32 s4, s101
	s_cbranch_scc0 .Lrms_loop

.LBB0_1037:
	s_or_b64 exec, exec, s[0:1]
	s_waitcnt lgkmcnt(0)
	v_lshrrev_b32_e32 v0, 5, v193
	v_and_b32_e32 v0, 30, v0
	s_and_b32 s7, s6, 7
	s_lshl_b32 s7, s7, 12
	s_lshr_b32 s98, s6, 3
	s_lshl_b32 s98, s98, 4
	s_add_i32 s98, s98, s7
	s_add_i32 s7, s7, 0xfff
	v_add_u32_e32 v144, s98, v0
	s_mov_b32 s0, 0x8000
	v_cmp_gt_i32_e64 s[4:5], s0, v144
	v_ashrrev_i32_e32 v145, 31, v144
	s_barrier
	s_and_saveexec_b64 s[24:25], s[4:5]
	s_cbranch_execz .LBB0_1040
	v_lshlrev_b32_e32 v16, 4, v192
	global_load_dwordx4 v[0:3], v16, s[46:47]
	global_load_dwordx4 v[4:7], v16, s[46:47] offset:1024
	global_load_dwordx4 v[8:11], v16, s[46:47] offset:2048
	global_load_dwordx4 v[12:15], v16, s[46:47] offset:3072
	v_mbcnt_hi_u32_b32 v16, -1, v226
	v_and_b32_e32 v17, 64, v16
	v_add_u32_e32 v17, 64, v17
	v_xor_b32_e32 v18, 1, v16
	v_cmp_lt_i32_e32 vcc, v18, v17
	s_lshl_b32 s26, s92, 1
	v_or_b32_e32 v22, 0x80, v192
	v_cndmask_b32_e32 v18, v16, v18, vcc
	v_lshlrev_b32_e32 v44, 2, v18
	v_xor_b32_e32 v18, 2, v16
	v_cmp_lt_i32_e32 vcc, v18, v17
	v_or_b32_e32 v24, 0xc0, v192
	s_mov_b64 s[0:1], 0x198f0e00
	v_cndmask_b32_e32 v18, v16, v18, vcc
	v_lshlrev_b32_e32 v45, 2, v18
	v_xor_b32_e32 v18, 4, v16
	v_cmp_lt_i32_e32 vcc, v18, v17
	s_ashr_i32 s27, s26, 31
	s_lshl_b64 s[28:29], s[26:27], 11
	v_cndmask_b32_e32 v18, v16, v18, vcc
	v_lshlrev_b32_e32 v46, 2, v18
	v_xor_b32_e32 v18, 8, v16
	v_cmp_lt_i32_e32 vcc, v18, v17
	s_mov_b64 s[30:31], 0
	s_mov_b64 s[36:37], 0x3000
	v_cndmask_b32_e32 v18, v16, v18, vcc
	v_lshlrev_b32_e32 v47, 2, v18
	v_xor_b32_e32 v18, 16, v16
	v_cmp_lt_i32_e32 vcc, v18, v17
	s_mov_b64 s[38:39], 0x4000
	v_lshlrev_b32_e32 v20, 4, v192
	v_cndmask_b32_e32 v18, v16, v18, vcc
	v_lshlrev_b32_e32 v48, 2, v18
	v_xor_b32_e32 v18, 32, v16
	v_cmp_lt_i32_e32 vcc, v18, v17
	v_mov_b32_e32 v17, 0
	v_lshlrev_b32_e32 v22, 4, v22
	v_cndmask_b32_e32 v16, v16, v18, vcc
	v_lshlrev_b64 v[18:19], 11, v[144:145]
	v_lshl_or_b32 v18, v192, 3, v18
	v_lshlrev_b32_e32 v49, 2, v16
	v_or_b32_e32 v16, 64, v192
	v_lshl_add_u64 v[18:19], s[90:91], 0, v[18:19]
	v_lshl_add_u64 v[18:19], v[18:19], 0, s[0:1]
	v_lshlrev_b32_e32 v16, 4, v16
	v_lshlrev_b32_e32 v24, 4, v24
	v_mov_b32_e32 v50, 0x358637bd
	s_mov_b32 s2, 0xf800000
	v_mov_b32_e32 v51, 0x260
	s_mov_b32 s3, 0xeb000000
	v_mov_b32_e32 v21, v17
	v_mov_b32_e32 v52, v144

.LBB0_1236:
	s_or_b64 exec, exec, s[0:1]
	s_and_b32 s10, s6, 7
	s_lshl_b32 s10, s10, 12
	s_add_i32 s10, s10, 0xfff
	s_waitcnt lgkmcnt(0)
	s_barrier
	s_and_saveexec_b64 s[0:1], s[4:5]
	s_cbranch_execz .LBB0_1239
	v_mbcnt_hi_u32_b32 v0, -1, v226
	v_and_b32_e32 v1, 64, v0
	v_add_u32_e32 v1, 64, v1
	v_xor_b32_e32 v2, 1, v0
	v_cmp_lt_i32_e32 vcc, v2, v1
	v_lshlrev_b64 v[4:5], 12, v[144:145]
	v_mov_b32_e32 v3, 0
	v_cndmask_b32_e32 v2, v0, v2, vcc
	v_lshlrev_b32_e32 v6, 2, v2
	v_xor_b32_e32 v2, 2, v0
	v_cmp_lt_i32_e32 vcc, v2, v1
	s_lshl_b32 s2, s92, 1
	s_mov_b64 s[0:1], 0x1000
	v_cndmask_b32_e32 v2, v0, v2, vcc
	v_lshlrev_b32_e32 v7, 2, v2
	v_xor_b32_e32 v2, 4, v0
	v_cmp_lt_i32_e32 vcc, v2, v1
	s_ashr_i32 s3, s2, 31
	s_lshl_b64 s[4:5], s[2:3], 12
	v_cndmask_b32_e32 v2, v0, v2, vcc
	v_lshlrev_b32_e32 v8, 2, v2
	v_xor_b32_e32 v2, 8, v0
	v_cmp_lt_i32_e32 vcc, v2, v1
	s_lshl_b64 s[6:7], s[2:3], 11
	s_mov_b64 s[8:9], 0
	v_cndmask_b32_e32 v2, v0, v2, vcc
	v_lshlrev_b32_e32 v9, 2, v2
	v_xor_b32_e32 v2, 16, v0
	v_cmp_lt_i32_e32 vcc, v2, v1
	v_mov_b32_e32 v12, 0x358637bd
	s_mov_b32 s3, 0xf800000
	v_cndmask_b32_e32 v2, v0, v2, vcc
	v_lshlrev_b32_e32 v10, 2, v2
	v_xor_b32_e32 v2, 32, v0
	v_cmp_lt_i32_e32 vcc, v2, v1
	v_mov_b32_e32 v13, 0x260
	v_cndmask_b32_e32 v0, v0, v2, vcc
	v_lshlrev_b32_e32 v2, 4, v192
	v_or_b32_e32 v4, v4, v2
	v_lshlrev_b32_e32 v11, 2, v0
	v_lshl_add_u64 v[0:1], s[86:87], 0, v[2:3]
	v_lshl_add_u64 v[2:3], s[88:89], 0, v[4:5]
	v_lshlrev_b64 v[4:5], 11, v[144:145]
	v_lshl_or_b32 v4, v192, 3, v4
	v_lshl_add_u64 v[2:3], v[2:3], 0, s[0:1]
	v_lshl_add_u64 v[4:5], s[90:91], 0, v[4:5]
	s_mov_b64 s[0:1], 0x48f0000
	v_lshl_add_u64 v[4:5], v[4:5], 0, s[0:1]
